# weight-copy tr_store: the 16 dependent norm-gain loads per item batched into one wait (P0 and attention-phase copier instances)
# baseline (speedup 1.0000x reference)
; #define LAS __attribute__((address_space(3)))
; __device__ __forceinline__ unsigned pk2(float lo, float hi) { return pg8::cvt_pk_bf16(lo, hi); }
; __device__ __forceinline__ void tr_store(const TrItem& t, const float (&tv)[32], LAS float* scr, int lane) {
;     const float* gp = t.gk ? t.gk + t.k0 + 32 * (lane >> 5) : nullptr; LAS unsigned* T = (LAS unsigned*)scr;
; #pragma unroll
;     for (int j = 0; j < 16; ++j) { float a = tv[2 * j], b = tv[2 * j + 1]; if (gp) { a *= gp[2 * j]; b *= gp[2 * j + 1]; } T[(16 * (lane >> 5) + j) * TR_P + (lane & 31)] = pk2(a, b); }
.LBB0_149:
	s_ashr_i32 s37, s36, 31
	s_lshl_b64 s[8:9], s[36:37], 2
	s_add_u32 s8, s40, s8
	s_addc_u32 s9, s41, s9
	v_mov_b32_e32 v29, v27
	s_cmp_lg_u64 s[40:41], 0
	v_lshl_add_u64 v[74:75], s[8:9], 0, v[28:29]
	s_cselect_b64 s[64:65], -1, 0
	s_cmp_eq_u64 s[40:41], 0
	s_cbranch_scc1 .Ltrgk_942
	global_load_dwordx2 v[96:97], v[74:75], off
	global_load_dwordx2 v[98:99], v[74:75], off offset:8
	global_load_dwordx2 v[100:101], v[74:75], off offset:16
	global_load_dwordx2 v[102:103], v[74:75], off offset:24
	global_load_dwordx2 v[104:105], v[74:75], off offset:32
	global_load_dwordx2 v[106:107], v[74:75], off offset:40
	global_load_dwordx2 v[108:109], v[74:75], off offset:48
	global_load_dwordx2 v[110:111], v[74:75], off offset:56
	global_load_dwordx2 v[112:113], v[74:75], off offset:64
	global_load_dwordx2 v[114:115], v[74:75], off offset:72
	global_load_dwordx2 v[116:117], v[74:75], off offset:80
	global_load_dwordx2 v[118:119], v[74:75], off offset:88
	global_load_dwordx2 v[120:121], v[74:75], off offset:96
	global_load_dwordx2 v[122:123], v[74:75], off offset:104
	global_load_dwordx2 v[124:125], v[74:75], off offset:112
	global_load_dwordx2 v[126:127], v[74:75], off offset:120
	s_waitcnt vmcnt(0)
.Ltrgk_942:
	s_cmp_eq_u64 s[40:41], 0
	s_waitcnt vmcnt(0)
	v_mov_b64_e32 v[76:77], v[4:5]
	s_cbranch_scc1 .LBB0_151
	v_mov_b64_e32 v[76:77], v[96:97]
	v_pk_mul_f32 v[76:77], v[4:5], v[76:77]
.LBB0_151:
	s_nop 0
	v_cvt_pk_bf16_f32 v29, v76, v77
	ds_write_b32 v81, v29
	v_cndmask_b32_e64 v29, 0, 1, s[64:65]
	v_cmp_ne_u32_e64 s[8:9], 1, v29
	s_andn2_b64 vcc, exec, s[64:65]
	v_mov_b64_e32 v[76:77], v[6:7]
	s_cbranch_vccnz .LBB0_153
	v_mov_b64_e32 v[76:77], v[98:99]
	v_pk_mul_f32 v[76:77], v[6:7], v[76:77]
.LBB0_153:
	s_nop 0
	v_cvt_pk_bf16_f32 v29, v76, v77
	s_and_b64 vcc, exec, s[8:9]
	v_mov_b64_e32 v[76:77], v[8:9]
	ds_write_b32 v81, v29 offset:136
	s_cbranch_vccnz .LBB0_155
	v_mov_b64_e32 v[76:77], v[100:101]
	v_pk_mul_f32 v[76:77], v[8:9], v[76:77]
.LBB0_155:
	s_nop 0
	v_cvt_pk_bf16_f32 v29, v76, v77
	s_and_b64 vcc, exec, s[8:9]
	v_mov_b64_e32 v[76:77], v[10:11]
	ds_write_b32 v81, v29 offset:272
	s_cbranch_vccnz .LBB0_157
	v_mov_b64_e32 v[76:77], v[102:103]
	v_pk_mul_f32 v[76:77], v[10:11], v[76:77]
.LBB0_157:
	s_nop 0
	v_cvt_pk_bf16_f32 v29, v76, v77
	s_and_b64 vcc, exec, s[8:9]
	v_mov_b64_e32 v[76:77], v[12:13]
	ds_write_b32 v81, v29 offset:408
	s_cbranch_vccnz .LBB0_159
	v_mov_b64_e32 v[76:77], v[104:105]
	v_pk_mul_f32 v[76:77], v[12:13], v[76:77]
.LBB0_159:
	s_nop 0
	v_cvt_pk_bf16_f32 v29, v76, v77
	s_and_b64 vcc, exec, s[8:9]
	v_mov_b64_e32 v[76:77], v[14:15]
	ds_write_b32 v81, v29 offset:544
	s_cbranch_vccnz .LBB0_161
	v_mov_b64_e32 v[76:77], v[106:107]
	v_pk_mul_f32 v[76:77], v[14:15], v[76:77]
.LBB0_161:
	s_nop 0
	v_cvt_pk_bf16_f32 v29, v76, v77
	s_and_b64 vcc, exec, s[8:9]
	v_mov_b64_e32 v[76:77], v[16:17]
	ds_write_b32 v81, v29 offset:680
	s_cbranch_vccnz .LBB0_163
	v_mov_b64_e32 v[76:77], v[108:109]
	v_pk_mul_f32 v[76:77], v[16:17], v[76:77]
.LBB0_163:
	s_nop 0
	v_cvt_pk_bf16_f32 v29, v76, v77
	s_and_b64 vcc, exec, s[8:9]
	v_mov_b64_e32 v[76:77], v[18:19]
	ds_write_b32 v81, v29 offset:816
	s_cbranch_vccnz .LBB0_165
	v_mov_b64_e32 v[76:77], v[110:111]
	v_pk_mul_f32 v[76:77], v[18:19], v[76:77]
.LBB0_165:
	s_nop 0
	v_cvt_pk_bf16_f32 v29, v76, v77
	s_and_b64 vcc, exec, s[8:9]
	v_mov_b64_e32 v[76:77], v[20:21]
	ds_write_b32 v81, v29 offset:952
	s_cbranch_vccnz .LBB0_167
	v_mov_b64_e32 v[76:77], v[112:113]
	v_pk_mul_f32 v[76:77], v[20:21], v[76:77]
.LBB0_167:
	s_nop 0
	v_cvt_pk_bf16_f32 v29, v76, v77
	s_and_b64 vcc, exec, s[8:9]
	v_mov_b64_e32 v[76:77], v[24:25]
	ds_write_b32 v81, v29 offset:1088
	s_cbranch_vccnz .LBB0_169
	v_mov_b64_e32 v[76:77], v[114:115]
	v_pk_mul_f32 v[76:77], v[24:25], v[76:77]
.LBB0_169:
	s_nop 0
	v_cvt_pk_bf16_f32 v29, v76, v77
	s_and_b64 vcc, exec, s[8:9]
	v_mov_b64_e32 v[76:77], v[30:31]
	ds_write_b32 v81, v29 offset:1224
	s_cbranch_vccnz .LBB0_171
	v_mov_b64_e32 v[76:77], v[116:117]
	v_pk_mul_f32 v[76:77], v[30:31], v[76:77]
.LBB0_171:
	s_nop 0
	v_cvt_pk_bf16_f32 v29, v76, v77
	s_and_b64 vcc, exec, s[8:9]
	v_mov_b64_e32 v[76:77], v[32:33]
	ds_write_b32 v81, v29 offset:1360
	s_cbranch_vccnz .LBB0_173
	v_mov_b64_e32 v[76:77], v[118:119]
	v_pk_mul_f32 v[76:77], v[32:33], v[76:77]
.LBB0_173:
	s_nop 0
	v_cvt_pk_bf16_f32 v29, v76, v77
	s_and_b64 vcc, exec, s[8:9]
	v_mov_b64_e32 v[76:77], v[38:39]
	ds_write_b32 v81, v29 offset:1496
	s_cbranch_vccnz .LBB0_175
	v_mov_b64_e32 v[76:77], v[120:121]
	v_pk_mul_f32 v[76:77], v[38:39], v[76:77]
.LBB0_175:
	s_nop 0
	v_cvt_pk_bf16_f32 v29, v76, v77
	s_and_b64 vcc, exec, s[8:9]
	v_mov_b64_e32 v[76:77], v[44:45]
	ds_write_b32 v81, v29 offset:1632
	s_cbranch_vccnz .LBB0_177
	v_mov_b64_e32 v[76:77], v[122:123]
	v_pk_mul_f32 v[76:77], v[44:45], v[76:77]
.LBB0_177:
	s_nop 0
	v_cvt_pk_bf16_f32 v29, v76, v77
	s_and_b64 vcc, exec, s[8:9]
	v_mov_b64_e32 v[76:77], v[52:53]
	ds_write_b32 v81, v29 offset:1768
	s_cbranch_vccnz .LBB0_179
	v_mov_b64_e32 v[76:77], v[124:125]
	v_pk_mul_f32 v[76:77], v[52:53], v[76:77]
.LBB0_179:
	s_nop 0
	v_cvt_pk_bf16_f32 v29, v76, v77
	s_and_b64 vcc, exec, s[8:9]
	v_mov_b64_e32 v[76:77], v[56:57]
	ds_write_b32 v81, v29 offset:1904
	s_cbranch_vccnz .LBB0_181
	v_mov_b64_e32 v[74:75], v[126:127]
	v_pk_mul_f32 v[76:77], v[56:57], v[74:75]

; #define LAS __attribute__((address_space(3)))
; __device__ __forceinline__ unsigned pk2(float lo, float hi) { return pg8::cvt_pk_bf16(lo, hi); }
; __device__ __forceinline__ void tr_store(const TrItem& t, const float (&tv)[32], LAS float* scr, int lane) {
;     const float* gp = t.gk ? t.gk + t.k0 + 32 * (lane >> 5) : nullptr; LAS unsigned* T = (LAS unsigned*)scr;
; #pragma unroll
;     for (int j = 0; j < 16; ++j) { float a = tv[2 * j], b = tv[2 * j + 1]; if (gp) { a *= gp[2 * j]; b *= gp[2 * j + 1]; } T[(16 * (lane >> 5) + j) * TR_P + (lane & 31)] = pk2(a, b); }
.LBB0_252:
	s_ashr_i32 s47, s46, 31
	s_lshl_b64 s[6:7], s[46:47], 2
	s_add_u32 s6, s50, s6
	s_addc_u32 s7, s51, s7
	v_mov_b32_e32 v29, v27
	s_cmp_lg_u64 s[50:51], 0
	v_lshl_add_u64 v[74:75], s[6:7], 0, v[28:29]
	s_cselect_b64 s[64:65], -1, 0
	s_cmp_eq_u64 s[50:51], 0
	s_cbranch_scc1 .Ltrgk_1560
	global_load_dwordx2 v[96:97], v[74:75], off
	global_load_dwordx2 v[98:99], v[74:75], off offset:8
	global_load_dwordx2 v[100:101], v[74:75], off offset:16
	global_load_dwordx2 v[102:103], v[74:75], off offset:24
	global_load_dwordx2 v[104:105], v[74:75], off offset:32
	global_load_dwordx2 v[106:107], v[74:75], off offset:40
	global_load_dwordx2 v[108:109], v[74:75], off offset:48
	global_load_dwordx2 v[110:111], v[74:75], off offset:56
	global_load_dwordx2 v[112:113], v[74:75], off offset:64
	global_load_dwordx2 v[114:115], v[74:75], off offset:72
	global_load_dwordx2 v[116:117], v[74:75], off offset:80
	global_load_dwordx2 v[118:119], v[74:75], off offset:88
	global_load_dwordx2 v[120:121], v[74:75], off offset:96
	global_load_dwordx2 v[122:123], v[74:75], off offset:104
	global_load_dwordx2 v[124:125], v[74:75], off offset:112
	global_load_dwordx2 v[126:127], v[74:75], off offset:120
	s_waitcnt vmcnt(0)
.Ltrgk_1560:
	s_cmp_eq_u64 s[50:51], 0
	v_mov_b32_e32 v76, v34
	v_mov_b32_e32 v77, v35
	s_cbranch_scc1 .LBB0_254
	v_mov_b64_e32 v[76:77], v[96:97]
	v_pk_mul_f32 v[76:77], v[34:35], v[76:77]
.LBB0_254:
	s_nop 0
	v_cvt_pk_bf16_f32 v29, v76, v77
	ds_write_b32 v81, v29
	v_cndmask_b32_e64 v29, 0, 1, s[64:65]
	v_cmp_ne_u32_e64 s[6:7], 1, v29
	s_andn2_b64 vcc, exec, s[64:65]
	v_mov_b32_e32 v76, v36
	v_mov_b32_e32 v77, v37
	s_cbranch_vccnz .LBB0_256
	v_mov_b64_e32 v[76:77], v[98:99]
	v_pk_mul_f32 v[76:77], v[36:37], v[76:77]
.LBB0_256:
	s_nop 0
	v_cvt_pk_bf16_f32 v29, v76, v77
	s_and_b64 vcc, exec, s[6:7]
	v_mov_b32_e32 v76, v40
	v_mov_b32_e32 v77, v41
	ds_write_b32 v81, v29 offset:136
	s_cbranch_vccnz .LBB0_258
	v_mov_b64_e32 v[76:77], v[100:101]
	v_pk_mul_f32 v[76:77], v[40:41], v[76:77]
.LBB0_258:
	s_nop 0
	v_cvt_pk_bf16_f32 v29, v76, v77
	s_and_b64 vcc, exec, s[6:7]
	v_mov_b32_e32 v76, v42
	v_mov_b32_e32 v77, v43
	ds_write_b32 v81, v29 offset:272
	s_cbranch_vccnz .LBB0_260
	v_mov_b64_e32 v[76:77], v[102:103]
	v_pk_mul_f32 v[76:77], v[42:43], v[76:77]
.LBB0_260:
	s_nop 0
	v_cvt_pk_bf16_f32 v29, v76, v77
	s_and_b64 vcc, exec, s[6:7]
	v_mov_b32_e32 v76, v46
	v_mov_b32_e32 v77, v47
	ds_write_b32 v81, v29 offset:408
	s_cbranch_vccnz .LBB0_262
	v_mov_b64_e32 v[76:77], v[104:105]
	v_pk_mul_f32 v[76:77], v[46:47], v[76:77]
.LBB0_262:
	s_nop 0
	v_cvt_pk_bf16_f32 v29, v76, v77
	s_and_b64 vcc, exec, s[6:7]
	v_mov_b32_e32 v76, v48
	v_mov_b32_e32 v77, v49
	ds_write_b32 v81, v29 offset:544
	s_cbranch_vccnz .LBB0_264
	v_mov_b64_e32 v[76:77], v[106:107]
	v_pk_mul_f32 v[76:77], v[48:49], v[76:77]
.LBB0_264:
	s_nop 0
	v_cvt_pk_bf16_f32 v29, v76, v77
	s_and_b64 vcc, exec, s[6:7]
	v_mov_b32_e32 v76, v50
	v_mov_b32_e32 v77, v51
	ds_write_b32 v81, v29 offset:680
	s_cbranch_vccnz .LBB0_266
	v_mov_b64_e32 v[76:77], v[108:109]
	v_pk_mul_f32 v[76:77], v[50:51], v[76:77]
.LBB0_266:
	s_nop 0
	v_cvt_pk_bf16_f32 v29, v76, v77
	s_and_b64 vcc, exec, s[6:7]
	v_mov_b32_e32 v76, v54
	v_mov_b32_e32 v77, v55
	ds_write_b32 v81, v29 offset:816
	s_cbranch_vccnz .LBB0_268
	v_mov_b64_e32 v[76:77], v[110:111]
	v_pk_mul_f32 v[76:77], v[54:55], v[76:77]
.LBB0_268:
	s_nop 0
	v_cvt_pk_bf16_f32 v29, v76, v77
	s_and_b64 vcc, exec, s[6:7]
	v_mov_b32_e32 v76, v58
	v_mov_b32_e32 v77, v59
	ds_write_b32 v81, v29 offset:952
	s_cbranch_vccnz .LBB0_270
	v_mov_b64_e32 v[76:77], v[112:113]
	v_pk_mul_f32 v[76:77], v[58:59], v[76:77]
.LBB0_270:
	s_nop 0
	v_cvt_pk_bf16_f32 v29, v76, v77
	s_and_b64 vcc, exec, s[6:7]
	v_mov_b32_e32 v76, v60
	v_mov_b32_e32 v77, v61
	ds_write_b32 v81, v29 offset:1088
	s_cbranch_vccnz .LBB0_272
	v_mov_b64_e32 v[76:77], v[114:115]
	v_pk_mul_f32 v[76:77], v[60:61], v[76:77]
.LBB0_272:
	s_nop 0
	v_cvt_pk_bf16_f32 v29, v76, v77
	s_and_b64 vcc, exec, s[6:7]
	v_mov_b32_e32 v76, v62
	v_mov_b32_e32 v77, v63
	ds_write_b32 v81, v29 offset:1224
	s_cbranch_vccnz .LBB0_274
	v_mov_b64_e32 v[76:77], v[116:117]
	v_pk_mul_f32 v[76:77], v[62:63], v[76:77]
.LBB0_274:
	s_nop 0
	v_cvt_pk_bf16_f32 v29, v76, v77
	s_and_b64 vcc, exec, s[6:7]
	v_mov_b32_e32 v76, v64
	v_mov_b32_e32 v77, v65
	ds_write_b32 v81, v29 offset:1360
	s_cbranch_vccnz .LBB0_276
	v_mov_b64_e32 v[76:77], v[118:119]
	v_pk_mul_f32 v[76:77], v[64:65], v[76:77]
.LBB0_276:
	s_nop 0
	v_cvt_pk_bf16_f32 v29, v76, v77
	s_and_b64 vcc, exec, s[6:7]
	v_mov_b32_e32 v76, v66
	v_mov_b32_e32 v77, v67
	ds_write_b32 v81, v29 offset:1496
	s_cbranch_vccnz .LBB0_278
	v_mov_b64_e32 v[76:77], v[120:121]
	v_pk_mul_f32 v[76:77], v[66:67], v[76:77]
.LBB0_278:
	s_nop 0
	v_cvt_pk_bf16_f32 v29, v76, v77
	s_and_b64 vcc, exec, s[6:7]
	v_mov_b32_e32 v76, v68
	v_mov_b32_e32 v77, v69
	ds_write_b32 v81, v29 offset:1632
	s_cbranch_vccnz .LBB0_280
	v_mov_b64_e32 v[76:77], v[122:123]
	v_pk_mul_f32 v[76:77], v[68:69], v[76:77]
.LBB0_280:
	s_nop 0
	v_cvt_pk_bf16_f32 v29, v76, v77
	s_and_b64 vcc, exec, s[6:7]
	v_mov_b32_e32 v76, v70
	v_mov_b32_e32 v77, v71
	ds_write_b32 v81, v29 offset:1768
	s_cbranch_vccnz .LBB0_282
	v_mov_b64_e32 v[76:77], v[124:125]
	v_pk_mul_f32 v[76:77], v[70:71], v[76:77]
.LBB0_282:
	s_nop 0
	v_cvt_pk_bf16_f32 v29, v76, v77
	s_and_b64 vcc, exec, s[6:7]
	v_mov_b32_e32 v76, v72
	v_mov_b32_e32 v77, v73
	ds_write_b32 v81, v29 offset:1904
	s_cbranch_vccnz .LBB0_78
	v_mov_b64_e32 v[74:75], v[126:127]
	v_pk_mul_f32 v[76:77], v[72:73], v[74:75]
	s_branch .LBB0_78

; #define LAS __attribute__((address_space(3)))
; __device__ __forceinline__ unsigned pk2(float lo, float hi) { return pg8::cvt_pk_bf16(lo, hi); }
; __device__ __forceinline__ void tr_store(const TrItem& t, const float (&tv)[32], LAS float* scr, int lane) {
;     const float* gp = t.gk ? t.gk + t.k0 + 32 * (lane >> 5) : nullptr; LAS unsigned* T = (LAS unsigned*)scr;
; #pragma unroll
;     for (int j = 0; j < 16; ++j) { float a = tv[2 * j], b = tv[2 * j + 1]; if (gp) { a *= gp[2 * j]; b *= gp[2 * j + 1]; } T[(16 * (lane >> 5) + j) * TR_P + (lane & 31)] = pk2(a, b); }
.LBB0_1448:
	s_ashr_i32 s39, s38, 31
	s_lshl_b64 s[8:9], s[38:39], 2
	s_add_u32 s8, s36, s8
	s_addc_u32 s9, s37, s9
	v_mov_b32_e32 v71, v3
	s_cmp_lg_u64 s[36:37], 0
	v_lshl_add_u64 v[74:75], s[8:9], 0, v[70:71]
	s_cselect_b64 s[14:15], -1, 0
	s_cmp_eq_u64 s[36:37], 0
	s_cbranch_scc1 .Ltrgk_23594
	global_load_dwordx2 v[106:107], v[74:75], off
	global_load_dwordx2 v[108:109], v[74:75], off offset:8
	global_load_dwordx2 v[110:111], v[74:75], off offset:16
	global_load_dwordx2 v[112:113], v[74:75], off offset:24
	global_load_dwordx2 v[114:115], v[74:75], off offset:32
	global_load_dwordx2 v[116:117], v[74:75], off offset:40
	global_load_dwordx2 v[118:119], v[74:75], off offset:48
	global_load_dwordx2 v[120:121], v[74:75], off offset:56
	global_load_dwordx2 v[122:123], v[74:75], off offset:64
	global_load_dwordx2 v[124:125], v[74:75], off offset:72
	global_load_dwordx2 v[126:127], v[74:75], off offset:80
	global_load_dwordx2 v[128:129], v[74:75], off offset:88
	global_load_dwordx2 v[170:171], v[74:75], off offset:96
	global_load_dwordx2 v[172:173], v[74:75], off offset:104
	global_load_dwordx2 v[174:175], v[74:75], off offset:112
	global_load_dwordx2 v[176:177], v[74:75], off offset:120
	s_waitcnt vmcnt(0)
.Ltrgk_23594:
	s_cmp_eq_u64 s[36:37], 0
	s_waitcnt vmcnt(0)
	v_mov_b32_e32 v76, v4
	v_mov_b32_e32 v77, v5
	s_cbranch_scc1 .LBB0_1450
	v_mov_b64_e32 v[76:77], v[106:107]
	v_pk_mul_f32 v[76:77], v[4:5], v[76:77]
.LBB0_1450:
	s_nop 0
	v_cvt_pk_bf16_f32 v1, v76, v77
	ds_write_b32 v84, v1
	v_cndmask_b32_e64 v1, 0, 1, s[14:15]
	v_cmp_ne_u32_e64 s[8:9], 1, v1
	s_andn2_b64 vcc, exec, s[14:15]
	v_mov_b32_e32 v76, v6
	v_mov_b32_e32 v77, v7
	s_cbranch_vccnz .LBB0_1452
	v_mov_b64_e32 v[76:77], v[108:109]
	v_pk_mul_f32 v[76:77], v[6:7], v[76:77]
.LBB0_1452:
	s_nop 0
	v_cvt_pk_bf16_f32 v1, v76, v77
	s_and_b64 vcc, exec, s[8:9]
	v_mov_b32_e32 v76, v8
	v_mov_b32_e32 v77, v9
	ds_write_b32 v84, v1 offset:136
	s_cbranch_vccnz .LBB0_1454
	v_mov_b64_e32 v[76:77], v[110:111]
	v_pk_mul_f32 v[76:77], v[8:9], v[76:77]
.LBB0_1454:
	s_nop 0
	v_cvt_pk_bf16_f32 v1, v76, v77
	s_and_b64 vcc, exec, s[8:9]
	v_mov_b32_e32 v76, v10
	v_mov_b32_e32 v77, v11
	ds_write_b32 v84, v1 offset:272
	s_cbranch_vccnz .LBB0_1456
	v_mov_b64_e32 v[76:77], v[112:113]
	v_pk_mul_f32 v[76:77], v[10:11], v[76:77]
.LBB0_1456:
	s_nop 0
	v_cvt_pk_bf16_f32 v1, v76, v77
	s_and_b64 vcc, exec, s[8:9]
	v_mov_b32_e32 v76, v12
	v_mov_b32_e32 v77, v13
	ds_write_b32 v84, v1 offset:408
	s_cbranch_vccnz .LBB0_1458
	v_mov_b64_e32 v[76:77], v[114:115]
	v_pk_mul_f32 v[76:77], v[12:13], v[76:77]
.LBB0_1458:
	s_nop 0
	v_cvt_pk_bf16_f32 v1, v76, v77
	s_and_b64 vcc, exec, s[8:9]
	v_mov_b32_e32 v76, v14
	v_mov_b32_e32 v77, v15
	ds_write_b32 v84, v1 offset:544
	s_cbranch_vccnz .LBB0_1460
	v_mov_b64_e32 v[76:77], v[116:117]
	v_pk_mul_f32 v[76:77], v[14:15], v[76:77]
.LBB0_1460:
	s_nop 0
	v_cvt_pk_bf16_f32 v1, v76, v77
	s_and_b64 vcc, exec, s[8:9]
	v_mov_b32_e32 v76, v16
	v_mov_b32_e32 v77, v17
	ds_write_b32 v84, v1 offset:680
	s_cbranch_vccnz .LBB0_1462
	v_mov_b64_e32 v[76:77], v[118:119]
	v_pk_mul_f32 v[76:77], v[16:17], v[76:77]
.LBB0_1462:
	s_nop 0
	v_cvt_pk_bf16_f32 v1, v76, v77
	s_and_b64 vcc, exec, s[8:9]
	v_mov_b32_e32 v76, v18
	v_mov_b32_e32 v77, v19
	ds_write_b32 v84, v1 offset:816
	s_cbranch_vccnz .LBB0_1464
	v_mov_b64_e32 v[76:77], v[120:121]
	v_pk_mul_f32 v[76:77], v[18:19], v[76:77]
.LBB0_1464:
	s_nop 0
	v_cvt_pk_bf16_f32 v1, v76, v77
	s_and_b64 vcc, exec, s[8:9]
	v_mov_b32_e32 v76, v20
	v_mov_b32_e32 v77, v21
	ds_write_b32 v84, v1 offset:952
	s_cbranch_vccnz .LBB0_1466
	v_mov_b64_e32 v[76:77], v[122:123]
	v_pk_mul_f32 v[76:77], v[20:21], v[76:77]
.LBB0_1466:
	s_nop 0
	v_cvt_pk_bf16_f32 v1, v76, v77
	s_and_b64 vcc, exec, s[8:9]
	v_mov_b32_e32 v76, v22
	v_mov_b32_e32 v77, v23
	ds_write_b32 v84, v1 offset:1088
	s_cbranch_vccnz .LBB0_1468
	v_mov_b64_e32 v[76:77], v[124:125]
	v_pk_mul_f32 v[76:77], v[22:23], v[76:77]
.LBB0_1468:
	s_nop 0
	v_cvt_pk_bf16_f32 v1, v76, v77
	s_and_b64 vcc, exec, s[8:9]
	v_mov_b32_e32 v76, v24
	v_mov_b32_e32 v77, v25
	ds_write_b32 v84, v1 offset:1224
	s_cbranch_vccnz .LBB0_1470
	v_mov_b64_e32 v[76:77], v[126:127]
	v_pk_mul_f32 v[76:77], v[24:25], v[76:77]
.LBB0_1470:
	s_nop 0
	v_cvt_pk_bf16_f32 v1, v76, v77
	s_and_b64 vcc, exec, s[8:9]
	v_mov_b32_e32 v76, v26
	v_mov_b32_e32 v77, v27
	ds_write_b32 v84, v1 offset:1360
	s_cbranch_vccnz .LBB0_1472
	v_mov_b64_e32 v[76:77], v[128:129]
	v_pk_mul_f32 v[76:77], v[26:27], v[76:77]
.LBB0_1472:
	s_nop 0
	v_cvt_pk_bf16_f32 v1, v76, v77
	s_and_b64 vcc, exec, s[8:9]
	v_mov_b32_e32 v76, v28
	v_mov_b32_e32 v77, v29
	ds_write_b32 v84, v1 offset:1496
	s_cbranch_vccnz .LBB0_1474
	v_mov_b64_e32 v[76:77], v[170:171]
	v_pk_mul_f32 v[76:77], v[28:29], v[76:77]
.LBB0_1474:
	s_nop 0
	v_cvt_pk_bf16_f32 v1, v76, v77
	s_and_b64 vcc, exec, s[8:9]
	v_mov_b32_e32 v76, v30
	v_mov_b32_e32 v77, v31
	ds_write_b32 v84, v1 offset:1632
	s_cbranch_vccnz .LBB0_1476
	v_mov_b64_e32 v[76:77], v[172:173]
	v_pk_mul_f32 v[76:77], v[30:31], v[76:77]
.LBB0_1476:
	s_nop 0
	v_cvt_pk_bf16_f32 v1, v76, v77
	s_and_b64 vcc, exec, s[8:9]
	v_mov_b32_e32 v76, v32
	v_mov_b32_e32 v77, v33
	ds_write_b32 v84, v1 offset:1768
	s_cbranch_vccnz .LBB0_1478
	v_mov_b64_e32 v[76:77], v[174:175]
	v_pk_mul_f32 v[76:77], v[32:33], v[76:77]
.LBB0_1478:
	s_nop 0
	v_cvt_pk_bf16_f32 v1, v76, v77
	s_and_b64 vcc, exec, s[8:9]
	v_mov_b32_e32 v76, v34
	v_mov_b32_e32 v77, v35
	ds_write_b32 v84, v1 offset:1904
	s_cbranch_vccnz .LBB0_1480
	v_mov_b64_e32 v[74:75], v[176:177]
	v_pk_mul_f32 v[76:77], v[34:35], v[74:75]

; #define LAS __attribute__((address_space(3)))
; __device__ __forceinline__ unsigned pk2(float lo, float hi) { return pg8::cvt_pk_bf16(lo, hi); }
; __device__ __forceinline__ void tr_store(const TrItem& t, const float (&tv)[32], LAS float* scr, int lane) {
;     const float* gp = t.gk ? t.gk + t.k0 + 32 * (lane >> 5) : nullptr; LAS unsigned* T = (LAS unsigned*)scr;
; #pragma unroll
;     for (int j = 0; j < 16; ++j) { float a = tv[2 * j], b = tv[2 * j + 1]; if (gp) { a *= gp[2 * j]; b *= gp[2 * j + 1]; } T[(16 * (lane >> 5) + j) * TR_P + (lane & 31)] = pk2(a, b); }
.LBB0_1550:
	s_ashr_i32 s27, s26, 31
	s_lshl_b64 s[6:7], s[26:27], 2
	s_add_u32 s6, s24, s6
	s_addc_u32 s7, s25, s7
	v_mov_b32_e32 v71, v3
	s_cmp_lg_u64 s[24:25], 0
	v_lshl_add_u64 v[74:75], s[6:7], 0, v[70:71]
	s_cselect_b64 s[14:15], -1, 0
	s_cmp_eq_u64 s[24:25], 0
	s_cbranch_scc1 .Ltrgk_24227
	global_load_dwordx2 v[106:107], v[74:75], off
	global_load_dwordx2 v[108:109], v[74:75], off offset:8
	global_load_dwordx2 v[110:111], v[74:75], off offset:16
	global_load_dwordx2 v[112:113], v[74:75], off offset:24
	global_load_dwordx2 v[114:115], v[74:75], off offset:32
	global_load_dwordx2 v[116:117], v[74:75], off offset:40
	global_load_dwordx2 v[118:119], v[74:75], off offset:48
	global_load_dwordx2 v[120:121], v[74:75], off offset:56
	global_load_dwordx2 v[122:123], v[74:75], off offset:64
	global_load_dwordx2 v[124:125], v[74:75], off offset:72
	global_load_dwordx2 v[126:127], v[74:75], off offset:80
	global_load_dwordx2 v[128:129], v[74:75], off offset:88
	global_load_dwordx2 v[170:171], v[74:75], off offset:96
	global_load_dwordx2 v[172:173], v[74:75], off offset:104
	global_load_dwordx2 v[174:175], v[74:75], off offset:112
	global_load_dwordx2 v[176:177], v[74:75], off offset:120
	s_waitcnt vmcnt(0)
.Ltrgk_24227:
	s_cmp_eq_u64 s[24:25], 0
	v_mov_b64_e32 v[76:77], v[36:37]
	s_cbranch_scc1 .LBB0_1552
	v_mov_b64_e32 v[76:77], v[106:107]
	v_pk_mul_f32 v[76:77], v[36:37], v[76:77]
.LBB0_1552:
	s_nop 0
	v_cvt_pk_bf16_f32 v1, v76, v77
	ds_write_b32 v84, v1
	v_cndmask_b32_e64 v1, 0, 1, s[14:15]
	v_cmp_ne_u32_e64 s[6:7], 1, v1
	s_andn2_b64 vcc, exec, s[14:15]
	v_mov_b64_e32 v[76:77], v[38:39]
	s_cbranch_vccnz .LBB0_1554
	v_mov_b64_e32 v[76:77], v[108:109]
	v_pk_mul_f32 v[76:77], v[38:39], v[76:77]
.LBB0_1554:
	s_nop 0
	v_cvt_pk_bf16_f32 v1, v76, v77
	s_and_b64 vcc, exec, s[6:7]
	v_mov_b64_e32 v[76:77], v[40:41]
	ds_write_b32 v84, v1 offset:136
	s_cbranch_vccnz .LBB0_1556
	v_mov_b64_e32 v[76:77], v[110:111]
	v_pk_mul_f32 v[76:77], v[40:41], v[76:77]
.LBB0_1556:
	s_nop 0
	v_cvt_pk_bf16_f32 v1, v76, v77
	s_and_b64 vcc, exec, s[6:7]
	v_mov_b64_e32 v[76:77], v[42:43]
	ds_write_b32 v84, v1 offset:272
	s_cbranch_vccnz .LBB0_1558
	v_mov_b64_e32 v[76:77], v[112:113]
	v_pk_mul_f32 v[76:77], v[42:43], v[76:77]
.LBB0_1558:
	s_nop 0
	v_cvt_pk_bf16_f32 v1, v76, v77
	s_and_b64 vcc, exec, s[6:7]
	v_mov_b64_e32 v[76:77], v[44:45]
	ds_write_b32 v84, v1 offset:408
	s_cbranch_vccnz .LBB0_1560
	v_mov_b64_e32 v[76:77], v[114:115]
	v_pk_mul_f32 v[76:77], v[44:45], v[76:77]
.LBB0_1560:
	s_nop 0
	v_cvt_pk_bf16_f32 v1, v76, v77
	s_and_b64 vcc, exec, s[6:7]
	v_mov_b64_e32 v[76:77], v[46:47]
	ds_write_b32 v84, v1 offset:544
	s_cbranch_vccnz .LBB0_1562
	v_mov_b64_e32 v[76:77], v[116:117]
	v_pk_mul_f32 v[76:77], v[46:47], v[76:77]
.LBB0_1562:
	s_nop 0
	v_cvt_pk_bf16_f32 v1, v76, v77
	s_and_b64 vcc, exec, s[6:7]
	v_mov_b64_e32 v[76:77], v[48:49]
	ds_write_b32 v84, v1 offset:680
	s_cbranch_vccnz .LBB0_1564
	v_mov_b64_e32 v[76:77], v[118:119]
	v_pk_mul_f32 v[76:77], v[48:49], v[76:77]
.LBB0_1564:
	s_nop 0
	v_cvt_pk_bf16_f32 v1, v76, v77
	s_and_b64 vcc, exec, s[6:7]
	v_mov_b64_e32 v[76:77], v[50:51]
	ds_write_b32 v84, v1 offset:816
	s_cbranch_vccnz .LBB0_1566
	v_mov_b64_e32 v[76:77], v[120:121]
	v_pk_mul_f32 v[76:77], v[50:51], v[76:77]
.LBB0_1566:
	s_nop 0
	v_cvt_pk_bf16_f32 v1, v76, v77
	s_and_b64 vcc, exec, s[6:7]
	v_mov_b64_e32 v[76:77], v[52:53]
	ds_write_b32 v84, v1 offset:952
	s_cbranch_vccnz .LBB0_1568
	v_mov_b64_e32 v[76:77], v[122:123]
	v_pk_mul_f32 v[76:77], v[52:53], v[76:77]
.LBB0_1568:
	s_nop 0
	v_cvt_pk_bf16_f32 v1, v76, v77
	s_and_b64 vcc, exec, s[6:7]
	v_mov_b64_e32 v[76:77], v[54:55]
	ds_write_b32 v84, v1 offset:1088
	s_cbranch_vccnz .LBB0_1570
	v_mov_b64_e32 v[76:77], v[124:125]
	v_pk_mul_f32 v[76:77], v[54:55], v[76:77]
.LBB0_1570:
	s_nop 0
	v_cvt_pk_bf16_f32 v1, v76, v77
	s_and_b64 vcc, exec, s[6:7]
	v_mov_b64_e32 v[76:77], v[56:57]
	ds_write_b32 v84, v1 offset:1224
	s_cbranch_vccnz .LBB0_1572
	v_mov_b64_e32 v[76:77], v[126:127]
	v_pk_mul_f32 v[76:77], v[56:57], v[76:77]
.LBB0_1572:
	s_nop 0
	v_cvt_pk_bf16_f32 v1, v76, v77
	s_and_b64 vcc, exec, s[6:7]
	v_mov_b64_e32 v[76:77], v[58:59]
	ds_write_b32 v84, v1 offset:1360
	s_cbranch_vccnz .LBB0_1574
	v_mov_b64_e32 v[76:77], v[128:129]
	v_pk_mul_f32 v[76:77], v[58:59], v[76:77]
.LBB0_1574:
	s_nop 0
	v_cvt_pk_bf16_f32 v1, v76, v77
	s_and_b64 vcc, exec, s[6:7]
	v_mov_b64_e32 v[76:77], v[60:61]
	ds_write_b32 v84, v1 offset:1496
	s_cbranch_vccnz .LBB0_1576
	v_mov_b64_e32 v[76:77], v[170:171]
	v_pk_mul_f32 v[76:77], v[60:61], v[76:77]
.LBB0_1576:
	s_nop 0
	v_cvt_pk_bf16_f32 v1, v76, v77
	s_and_b64 vcc, exec, s[6:7]
	v_mov_b64_e32 v[76:77], v[62:63]
	ds_write_b32 v84, v1 offset:1632
	s_cbranch_vccnz .LBB0_1578
	v_mov_b64_e32 v[76:77], v[172:173]
	v_pk_mul_f32 v[76:77], v[62:63], v[76:77]
.LBB0_1578:
	s_nop 0
	v_cvt_pk_bf16_f32 v1, v76, v77
	s_and_b64 vcc, exec, s[6:7]
	v_mov_b64_e32 v[76:77], v[66:67]
	ds_write_b32 v84, v1 offset:1768
	s_cbranch_vccnz .LBB0_1580
	v_mov_b64_e32 v[76:77], v[174:175]
	v_pk_mul_f32 v[76:77], v[66:67], v[76:77]
.LBB0_1580:
	s_nop 0
	v_cvt_pk_bf16_f32 v1, v76, v77
	s_and_b64 vcc, exec, s[6:7]
	v_mov_b64_e32 v[76:77], v[64:65]
	ds_write_b32 v84, v1 offset:1904
	s_cbranch_vccnz .LBB0_1582
	v_mov_b64_e32 v[74:75], v[176:177]
	v_pk_mul_f32 v[76:77], v[64:65], v[74:75]
